# hand-written pipelined weight conversion (3 tiles in flight, 2 LDS buffers, k-consecutive tiles per chunk), layer-1 conversion deferred to layer-0 up-phase tail, parallel first-barrier counter loads
# speedup vs baseline: 1.0068x; 1.0068x over previous
; DI unsigned xb_ld(unsigned* p) { return __hip_atomic_load(p, __ATOMIC_RELAXED, __HIP_MEMORY_SCOPE_AGENT); }
; DI void xcd_barrier_complete(unsigned* bar, unsigned x, unsigned& nloc, unsigned& nx) {
;     ...
;   for (;;) {
;     sum = 0u; cnt = 0u; mine = 0u;
; #pragma unroll
;     for (unsigned j = 0; j < 16; ++j) { const unsigned c = xb_ld(&bar[XB_XCNT(j)]); sum += c; cnt += (c > 0u) ? 1u : 0u; mine = (j == x) ? c : mine; }
;     if (sum == G) break;
;     __builtin_amdgcn_s_sleep(1);
;     if ((++sp & 255u) == 0u) { if (xb_ld(&bar[XB_TMO])) break; if (sp > XB_SPIN_CAP) { atomicAdd(&bar[XB_TMO], 1u); break; } }
;   }
;   nloc = mine > 0u ? mine : 1u; nx = cnt > 0u ? cnt : 1u;
.LBB0_27:
	global_load_dword v2, v209, s[88:89] sc1
	global_load_dword v0, v209, s[88:89] offset:256 sc1
	global_load_dword v1, v209, s[88:89] offset:512 sc1
	global_load_dword v3, v209, s[88:89] offset:768 sc1
	global_load_dword v4, v209, s[88:89] offset:1024 sc1
	global_load_dword v5, v209, s[88:89] offset:1280 sc1
	global_load_dword v6, v209, s[88:89] offset:1536 sc1
	global_load_dword v7, v209, s[88:89] offset:1792 sc1
	global_load_dword v8, v209, s[88:89] offset:2048 sc1
	global_load_dword v9, v209, s[88:89] offset:2304 sc1
	global_load_dword v10, v209, s[88:89] offset:2560 sc1
	global_load_dword v11, v209, s[88:89] offset:2816 sc1
	global_load_dword v12, v209, s[88:89] offset:3072 sc1
	global_load_dword v13, v209, s[88:89] offset:3328 sc1
	global_load_dword v14, v209, s[88:89] offset:3584 sc1
	global_load_dword v15, v209, s[88:89] offset:3840 sc1
	s_mov_b64 s[20:21], -1
	s_mov_b64 s[2:3], -1
	s_waitcnt vmcnt(0) lgkmcnt(0)
	v_add_u32_e32 v16, v0, v2
	v_add_u32_e32 v16, v16, v1
	v_add_u32_e32 v16, v16, v3
	v_add_u32_e32 v16, v16, v4
	v_add_u32_e32 v16, v16, v5
	v_add_u32_e32 v16, v16, v6
	v_add_u32_e32 v16, v16, v7
	v_add_u32_e32 v16, v16, v8
	v_add_u32_e32 v16, v16, v9
	v_add_u32_e32 v16, v16, v10
	v_add_u32_e32 v16, v16, v11
	v_add_u32_e32 v16, v16, v12
	v_add_u32_e32 v16, v16, v13
	v_add_u32_e32 v16, v16, v14
	v_add_u32_e32 v16, v16, v15
	v_cmp_eq_u32_e32 vcc, s56, v16
	s_cbranch_vccnz .LBB0_26
	s_and_b32 s2, s5, 0xff
	s_cmp_eq_u32 s2, 0
	s_mov_b64 s[2:3], -1
	s_mov_b64 s[22:23], -1
	s_sleep 1
	s_cbranch_scc0 .LBB0_31
	v_readlane_b32 s2, v252, 9
	v_readlane_b32 s3, v252, 10
	s_nop 4
	global_load_dword v16, v209, s[2:3] sc1
	s_waitcnt vmcnt(0)
	v_cmp_eq_u32_e32 vcc, 0, v16
	s_cbranch_vccnz .LBB0_33
	s_mov_b64 s[22:23], 0
	s_mov_b64 s[2:3], -1

; #define LAS __attribute__((address_space(3)))
; DI unsigned cvt_pk_bf16(float lo, float hi) { unsigned r; asm volatile("v_cvt_pk_bf16_f32 %0, %1, %2" : "=v"(r) : "v"(lo), "v"(hi)); return r; }
; template <bool GV_INTERLEAVE = false>
; DI void convert_chunk(const Ctx& cx, const float* __restrict__ src, bf16_t* __restrict__ dst, int K, int N, int tile0, int ntile, LAS unsigned char* lds, const float* __restrict__ gk = nullptr) {
;     ...
;       for (int i = 0; i < 4; ++i) L[(4 * n4 + i) * 66 + ((16 * j + kp) ^ ((n4 & 7) << 1))] = cvt_pk_bf16(v[j][0][i], v[j][1][i]);
;     if (c + 1 < ntile) { const int t2 = tile + 1, tn2 = t2 % tilesN, tk2 = t2 / tilesN;
; #pragma unroll
;       for (int j = 0; j < 4; ++j)
; #pragma unroll
;         for (int r = 0; r < 2; ++r) v[j][r] = __builtin_nontemporal_load((const f32x4*)(src + (size_t)(tk2 * 128 + 32 * j + 2 * kp + r) * N + tn2 * 128 + 4 * n4)); }
;     __syncthreads();
; #pragma unroll
;     for (int h2 = 0; h2 < 2; ++h2) {
;       const int rn = (tid >> 3) + 64 * h2, rc = tid & 7;
;       const int sw = ((rn >> 2) & 7) << 1;
;       u32x2 a0 = *(LAS u32x2*)(L + rn * 66 + ((8 * rc) ^ sw)), a1 = *(LAS u32x2*)(L + rn * 66 + ((8 * rc + 2) ^ sw));
;       u32x2 a2 = *(LAS u32x2*)(L + rn * 66 + ((8 * rc + 4) ^ sw)), a3 = *(LAS u32x2*)(L + rn * 66 + ((8 * rc + 6) ^ sw));
.LBB0_153:
	v_lshlrev_b32_e32 v1, 2, v242
	v_and_b32_e32 v2, 7, v242
	v_lshrrev_b32_e32 v3, 4, v242
	v_ashrrev_i32_e32 v0, 5, v242
	v_and_b32_e32 v32, 0x7c, v1
	v_lshlrev_b32_e32 v1, 1, v242
	v_and_b32_e32 v4, 14, v3
	v_lshlrev_b32_e32 v5, 3, v2
	v_bitop3_b32 v3, v5, v3, 14 bitop3:0x78
	v_bitop3_b32 v6, v5, v4, 2 bitop3:0x36
	v_bitop3_b32 v7, v5, v4, 4 bitop3:0x36
	v_bitop3_b32 v4, v5, v4, 6 bitop3:0x36
	v_bitop3_b32 v5, v1, v0, 14 bitop3:0x6c
	v_lshlrev_b32_e32 v5, 2, v5
	s_waitcnt lgkmcnt(0)
	v_mul_u32_u24_e32 v8, 0x108, v32
	v_add3_u32 v43, 0, v5, v8
	v_add_u32_e32 v5, 16, v0
	v_bitop3_b32 v5, v5, v1, 14 bitop3:0x78
	v_lshlrev_b32_e32 v5, 2, v5
	v_lshlrev_b32_e32 v33, 1, v0
	v_add3_u32 v44, 0, v5, v8
	v_add_u32_e32 v5, 32, v0
	v_add_u32_e32 v0, 48, v0
	v_ashrrev_i32_e32 v35, 3, v242
	s_movk_i32 s10, 0x108
	v_bitop3_b32 v0, v0, v1, 14 bitop3:0x78
	v_lshlrev_b32_e32 v34, 4, v2
	v_mul_lo_u32 v2, v35, s10
	v_lshlrev_b32_e32 v0, 2, v0
	v_add_u32_e32 v2, 0, v2
	v_lshlrev_b32_e32 v3, 2, v3
	v_bitop3_b32 v5, v5, v1, 14 bitop3:0x78
	v_add3_u32 v46, 0, v0, v8
	v_lshlrev_b32_e32 v0, 2, v6
	v_lshlrev_b32_e32 v1, 2, v7
	v_lshlrev_b32_e32 v4, 2, v4
	s_add_u32 s0, s2, 0x2a500000
	v_add_u32_e32 v42, v2, v3
	v_lshlrev_b32_e32 v5, 2, v5
	v_add_u32_e32 v47, v2, v0
	v_add_u32_e32 v48, v2, v1
	v_add_u32_e32 v49, v2, v4
	v_add_u32_e32 v50, 64, v35
	v_add_u32_e32 v2, 0x4200, v2
	s_addc_u32 s1, s3, 0
	s_cmp_eq_u32 s19, 1
	s_cselect_b32 s11, 0, 4
	s_or_b32 s0, s0, s11
	v_cmp_eq_u32_e64 s[34:35], 0, v242
	v_add3_u32 v45, 0, v5, v8
	v_add_u32_e32 v51, v2, v3
	v_add_u32_e32 v52, v2, v0
	v_add_u32_e32 v53, v2, v1
	v_add_u32_e32 v54, v2, v4
	v_and_b32_e32 v55, 0x7f, v35
	v_and_b32_e32 v56, 0x7f, v50
	s_branch .LBB0_157
.LBB0_156:
	s_and_b64 vcc, exec, s[22:23]
	s_cbranch_vccnz .LBB0_213

; DI void run_phase(const Params& p, int ph, LAS unsigned char* lds, int wid_s) {
;     ...
;       const int t0 = (NCHUNK - 1 - chunk) * CH, l = t0 >= PER_LAYER ? 1 : 0, u0 = t0 - l * PER_LAYER;
;       unsigned char* wl = ws + (size_t)l * WL_SIZE;
;       { const int u = u0;
;         if (u < 768) convert_chunk(cx, p.in[3] + (size_t)l * 2048 * IN_W, (bf16_t*)(wl + WL_WING), 2048, IN_W, u, CH, lds, p.in[2] + (size_t)l * 2048);
;         else if (u < 1536) convert_chunk(cx, p.in[9] + (size_t)l * 2048 * IN_W, (bf16_t*)(wl + WL_WING) + (size_t)IN_W * 2048, 2048, IN_W, u - 768, CH, lds, p.in[2] + (size_t)l * 2048);
;         else if (u < 1664) convert_chunk(cx, p.in[11] + (size_t)l * 1024 * 2048, (bf16_t*)(wl + WL_WBR), 1024, 2048, u - 1536, CH, lds);
;         else if (u < 1792) convert_chunk(cx, p.in[12] + (size_t)l * 1024 * 2048, (bf16_t*)(wl + WL_WBR) + (size_t)2048 * 1024, 1024, 2048, u - 1664, CH, lds);
;         else if (u < 1920) convert_chunk(cx, p.in[13] + (size_t)l * 1024 * 2048, (bf16_t*)(wl + WL_WBR) + (size_t)2 * 2048 * 1024, 1024, 2048, u - 1792, CH, lds);
;         else if (u < 2176) convert_chunk(cx, p.in[14] + (size_t)l * 2048 * 2048, (bf16_t*)(wl + WL_WOUT), 2048, 2048, u - 1920, CH, lds);
;         else if (u < 3584) convert_chunk<true>(cx, p.in[17] + (size_t)l * 2048 * UPW, (bf16_t*)(wl + WL_WUP), 2048, UPW, u - 2176, CH, lds, p.in[16] + (size_t)l * 2048);
;         else convert_chunk(cx, p.in[20] + (size_t)l * D_FF * 2048, (bf16_t*)(wl + WL_WDOWN), D_FF, 2048, u - 3584, CH, lds);
.Lcv_body:
	s_sub_i32 s10, 0x85f, s10
	s_lshl_b32 s10, s10, 2
	s_cmpk_gt_i32 s10, 0x10bf
	s_cselect_b32 s11, 0x10c0, 0
	s_cselect_b32 s12, 0x8e00000, 0
	s_cselect_b32 s83, 1, 0
	s_sub_i32 s10, s10, s11
	s_add_u32 s72, s2, s12
	s_addc_u32 s73, s3, 0
	s_cmpk_lt_i32 s10, 0x300
	s_cbranch_scc1 .Lcv_v0
	s_cmpk_lt_i32 s10, 0x600
	s_cbranch_scc1 .Lcv_v1
	s_cmpk_lt_i32 s10, 0x680
	s_cbranch_scc1 .Lcv_v2
	s_cmpk_lt_i32 s10, 0x700
	s_cbranch_scc1 .Lcv_v3
	s_cmpk_lt_i32 s10, 0x780
	s_cbranch_scc1 .Lcv_v4
	s_cmpk_lt_i32 s10, 0x880
	s_cbranch_scc1 .Lcv_v5
	s_cmpk_lt_i32 s10, 0xe00
	s_cbranch_scc1 .Lcv_v6
	s_branch .Lcv_v7
.Lcv_v0:
	v_readlane_b32 s68, v254, 16
	v_readlane_b32 s69, v254, 17
	v_readlane_b32 s70, v254, 14
	v_readlane_b32 s71, v254, 15
	s_mul_i32 s11, s83, 0x3000000
	s_add_u32 s68, s68, s11
	s_addc_u32 s69, s69, 0
	s_lshl_b32 s12, s83, 13
	s_add_u32 s70, s70, s12
	s_addc_u32 s71, s71, 0
	s_mov_b32 s41, 1
	s_mov_b32 s36, 0x80000
	s_mov_b32 s37, 0x300000
	s_mov_b32 s38, 0x6000
	s_mov_b32 s40, 48
	s_lshr_b32 s10, s10, 2
	s_lshr_b32 s31, s10, 4
	s_mul_i32 s31, s31, 0xaaab
	s_lshr_b32 s31, s31, 17
	s_mul_i32 s11, s31, 48
	s_sub_i32 s30, s10, s11
	s_lshl_b32 s31, s31, 2
	s_branch .Lcv_common
.Lcv_v1:
	v_readlane_b32 s68, v253, 27
	v_readlane_b32 s69, v253, 28
	v_readlane_b32 s70, v254, 14
	v_readlane_b32 s71, v254, 15
	s_mul_i32 s11, s83, 0x3000000
	s_add_u32 s68, s68, s11
	s_addc_u32 s69, s69, 0
	s_lshl_b32 s12, s83, 13
	s_add_u32 s70, s70, s12
	s_addc_u32 s71, s71, 0
	s_mov_b32 s41, 1
	s_add_u32 s72, s72, 0x1800000
	s_addc_u32 s73, s73, 0
	s_mov_b32 s36, 0x80000
	s_mov_b32 s37, 0x300000
	s_mov_b32 s38, 0x6000
	s_mov_b32 s40, 48
	s_sub_i32 s10, s10, 0x300
	s_lshr_b32 s10, s10, 2
	s_lshr_b32 s31, s10, 4
	s_mul_i32 s31, s31, 0xaaab
	s_lshr_b32 s31, s31, 17
	s_mul_i32 s11, s31, 48
	s_sub_i32 s30, s10, s11
	s_lshl_b32 s31, s31, 2
	s_branch .Lcv_common
.Lcv_v2:
	v_readlane_b32 s68, v253, 31
	v_readlane_b32 s69, v253, 32
	s_mul_i32 s11, s83, 0x800000
	s_add_u32 s68, s68, s11
	s_addc_u32 s69, s69, 0
	s_mov_b32 s70, s68
	s_mov_b32 s71, s69
	s_mov_b32 s41, 0
	s_add_u32 s72, s72, 0x3800000
	s_addc_u32 s73, s73, 0
	s_mov_b32 s36, 0x40000
	s_mov_b32 s37, 0x100000
	s_mov_b32 s38, 0x2000
	s_mov_b32 s40, 16
	s_sub_i32 s10, s10, 0x600
	s_lshr_b32 s10, s10, 2
	s_lshr_b32 s31, s10, 4
	s_and_b32 s30, s10, 15
	s_lshl_b32 s31, s31, 2
	s_branch .Lcv_common
.Lcv_v3:
	v_readlane_b32 s68, v253, 33
	v_readlane_b32 s69, v253, 34
	s_mul_i32 s11, s83, 0x800000
	s_add_u32 s68, s68, s11
	s_addc_u32 s69, s69, 0
	s_mov_b32 s70, s68
	s_mov_b32 s71, s69
	s_mov_b32 s41, 0
	s_add_u32 s72, s72, 0x3c00000
	s_addc_u32 s73, s73, 0
	s_mov_b32 s36, 0x40000
	s_mov_b32 s37, 0x100000
	s_mov_b32 s38, 0x2000
	s_mov_b32 s40, 16
	s_sub_i32 s10, s10, 0x680
	s_lshr_b32 s10, s10, 2
	s_lshr_b32 s31, s10, 4
	s_and_b32 s30, s10, 15
	s_lshl_b32 s31, s31, 2
	s_branch .Lcv_common
.Lcv_v4:
	v_readlane_b32 s68, v253, 35
	v_readlane_b32 s69, v253, 36
	s_mul_i32 s11, s83, 0x800000
	s_add_u32 s68, s68, s11
	s_addc_u32 s69, s69, 0
	s_mov_b32 s70, s68
	s_mov_b32 s71, s69
	s_mov_b32 s41, 0
	s_add_u32 s72, s72, 0x4000000
	s_addc_u32 s73, s73, 0
	s_mov_b32 s36, 0x40000
	s_mov_b32 s37, 0x100000
	s_mov_b32 s38, 0x2000
	s_mov_b32 s40, 16
	s_sub_i32 s10, s10, 0x700
	s_lshr_b32 s10, s10, 2
	s_lshr_b32 s31, s10, 4
	s_and_b32 s30, s10, 15
	s_lshl_b32 s31, s31, 2
	s_branch .Lcv_common
.Lcv_v5:
	v_readlane_b32 s68, v253, 37
	v_readlane_b32 s69, v253, 38
	s_mul_i32 s11, s83, 0x1000000
	s_add_u32 s68, s68, s11
	s_addc_u32 s69, s69, 0
	s_mov_b32 s70, s68
	s_mov_b32 s71, s69
	s_mov_b32 s41, 0
	s_add_u32 s72, s72, 0x4400000
	s_addc_u32 s73, s73, 0
	s_mov_b32 s36, 0x80000
	s_mov_b32 s37, 0x100000
	s_mov_b32 s38, 0x2000
	s_mov_b32 s40, 16
	s_sub_i32 s10, s10, 0x780
	s_lshr_b32 s10, s10, 2
	s_lshr_b32 s31, s10, 4
	s_and_b32 s30, s10, 15
	s_lshl_b32 s31, s31, 2
	s_branch .Lcv_common
.Lcv_v6:
	s_mov_b32 s68, s54
	s_mov_b32 s69, s55
	s_mov_b32 s70, s52
	s_mov_b32 s71, s53
	s_mul_i32 s11, s83, 0x5800000
	s_add_u32 s68, s68, s11
	s_addc_u32 s69, s69, 0
	s_lshl_b32 s12, s83, 13
	s_add_u32 s70, s70, s12
	s_addc_u32 s71, s71, 0
	s_mov_b32 s41, 3
	s_add_u32 s72, s72, 0x4c00000
	s_addc_u32 s73, s73, 0
	s_mov_b32 s36, 0x80000
	s_mov_b32 s37, 0x580000
	s_mov_b32 s38, 0xb000
	s_mov_b32 s40, 88
	s_sub_i32 s10, s10, 0x880
	s_lshr_b32 s10, s10, 2
	s_lshr_b32 s31, s10, 3
	s_mul_i32 s31, s31, 0xba2f
	s_lshr_b32 s31, s31, 19
	s_mul_i32 s11, s31, 0x58
	s_sub_i32 s30, s10, s11
	s_lshl_b32 s31, s31, 2
	s_branch .Lcv_common
.Lcv_v7:
	s_mov_b32 s68, s60
	s_mov_b32 s69, s61
	s_mul_i32 s11, s83, 0x2c00000
	s_add_u32 s68, s68, s11
	s_addc_u32 s69, s69, 0
	s_mov_b32 s70, s68
	s_mov_b32 s71, s69
	s_mov_b32 s41, 0
	s_add_u32 s72, s72, 0x7800000
	s_addc_u32 s73, s73, 0
	s_mov_b32 s36, 0x160000
	s_mov_b32 s37, 0x100000
	s_mov_b32 s38, 0x2000
	s_mov_b32 s40, 16
	s_sub_i32 s10, s10, 0xe00
	s_lshr_b32 s10, s10, 2
	s_lshr_b32 s31, s10, 4
	s_and_b32 s30, s10, 15
	s_lshl_b32 s31, s31, 2
; DI unsigned cvt_pk_bf16(float lo, float hi) { unsigned r; asm volatile("v_cvt_pk_bf16_f32 %0, %1, %2" : "=v"(r) : "v"(lo), "v"(hi)); return r; }
; template <bool GV_INTERLEAVE = false>
; DI void convert_chunk(const Ctx& cx, const float* __restrict__ src, bf16_t* __restrict__ dst, int K, int N, int tile0, int ntile, LAS unsigned char* lds, const float* __restrict__ gk = nullptr) {
;     ...
;   { const int tn = tile0 % tilesN, tk = tile0 / tilesN;
; #pragma unroll
;     for (int j = 0; j < 4; ++j)
; #pragma unroll
;       for (int r = 0; r < 2; ++r) v[j][r] = __builtin_nontemporal_load((const f32x4*)(src + (size_t)(tk * 128 + 32 * j + 2 * kp + r) * N + tn * 128 + 4 * n4)); }
;   for (int c = 0; c < ntile; ++c) {
;     const int tile = tile0 + c;
;     const int tn = tile % tilesN, tk = tile / tilesN;
;     const int k0 = tk * 128, n0 = tn * 128;
;     if (gk) {
; #pragma unroll
;       for (int j = 0; j < 4; ++j)
; #pragma unroll
;         for (int r = 0; r < 2; ++r) { const float g = gk[k0 + 32 * j + 2 * kp + r]; v[j][r] *= g; } }
;     __syncthreads();
; #pragma unroll
;     for (int j = 0; j < 4; ++j)
; #pragma unroll
;       for (int i = 0; i < 4; ++i) L[(4 * n4 + i) * 66 + ((16 * j + kp) ^ ((n4 & 7) << 1))] = cvt_pk_bf16(v[j][0][i], v[j][1][i]);
;     if (c + 1 < ntile) { const int t2 = tile + 1, tn2 = t2 % tilesN, tk2 = t2 / tilesN;
; #pragma unroll
;       for (int j = 0; j < 4; ++j)
; #pragma unroll
;         for (int r = 0; r < 2; ++r) v[j][r] = __builtin_nontemporal_load((const f32x4*)(src + (size_t)(tk2 * 128 + 32 * j + 2 * kp + r) * N + tn2 * 128 + 4 * n4)); }
.Lcv_common:
	s_mov_b32 s42, s30
	s_mov_b32 s43, s31
	s_lshr_b32 s82, s36, 1
	s_lshr_b32 s11, s36, 7
	v_mul_lo_u32 v184, v33, s38
	v_mul_lo_u32 v185, v35, s11
	v_lshlrev_b32_e32 v186, 2, v33
	v_lshl_add_u32 v184, v32, 2, v184
	v_lshl_add_u32 v185, v34, 1, v185
	s_mul_i32 s11, s31, s37
	s_lshl_b32 s12, s30, 9
	s_add_u32 s11, s11, s12
	s_add_u32 s74, s68, s11
	s_addc_u32 s75, s69, 0
	s_lshl_b32 s12, s31, 9
	s_add_u32 s80, s70, s12
	s_addc_u32 s81, s71, 0
	s_lshl_b32 s12, s38, 5
	global_load_dwordx2 v[160:161], v186, s[80:81]
	global_load_dwordx2 v[162:163], v186, s[80:81] offset:128
	global_load_dwordx2 v[164:165], v186, s[80:81] offset:256
	global_load_dwordx2 v[166:167], v186, s[80:81] offset:384
	global_load_dwordx4 v[64:67], v184, s[74:75] nt
	s_add_u32 s24, s74, s38
	s_addc_u32 s25, s75, 0
	global_load_dwordx4 v[68:71], v184, s[24:25] nt
	s_add_u32 s74, s74, s12
	s_addc_u32 s75, s75, 0
	global_load_dwordx4 v[72:75], v184, s[74:75] nt
	s_add_u32 s24, s74, s38
	s_addc_u32 s25, s75, 0
	global_load_dwordx4 v[76:79], v184, s[24:25] nt
	s_add_u32 s74, s74, s12
	s_addc_u32 s75, s75, 0
	global_load_dwordx4 v[80:83], v184, s[74:75] nt
	s_add_u32 s24, s74, s38
	s_addc_u32 s25, s75, 0
	global_load_dwordx4 v[84:87], v184, s[24:25] nt
	s_add_u32 s74, s74, s12
	s_addc_u32 s75, s75, 0
	global_load_dwordx4 v[88:91], v184, s[74:75] nt
	s_add_u32 s24, s74, s38
	s_addc_u32 s25, s75, 0
	global_load_dwordx4 v[92:95], v184, s[24:25] nt
	s_add_i32 s31, s31, 1
	s_mul_i32 s11, s31, s37
	s_lshl_b32 s12, s30, 9
	s_add_u32 s11, s11, s12
	s_add_u32 s74, s68, s11
	s_addc_u32 s75, s69, 0
	s_lshl_b32 s12, s31, 9
	s_add_u32 s80, s70, s12
	s_addc_u32 s81, s71, 0
	s_lshl_b32 s12, s38, 5
	global_load_dwordx2 v[168:169], v186, s[80:81]
	global_load_dwordx2 v[170:171], v186, s[80:81] offset:128
	global_load_dwordx2 v[172:173], v186, s[80:81] offset:256
	global_load_dwordx2 v[174:175], v186, s[80:81] offset:384
	global_load_dwordx4 v[96:99], v184, s[74:75] nt
	s_add_u32 s24, s74, s38
	s_addc_u32 s25, s75, 0
	global_load_dwordx4 v[100:103], v184, s[24:25] nt
	s_add_u32 s74, s74, s12
	s_addc_u32 s75, s75, 0
	global_load_dwordx4 v[104:107], v184, s[74:75] nt
	s_add_u32 s24, s74, s38
	s_addc_u32 s25, s75, 0
	global_load_dwordx4 v[108:111], v184, s[24:25] nt
	s_add_u32 s74, s74, s12
	s_addc_u32 s75, s75, 0
	global_load_dwordx4 v[112:115], v184, s[74:75] nt
	s_add_u32 s24, s74, s38
	s_addc_u32 s25, s75, 0
	global_load_dwordx4 v[116:119], v184, s[24:25] nt
	s_add_u32 s74, s74, s12
	s_addc_u32 s75, s75, 0
	global_load_dwordx4 v[120:123], v184, s[74:75] nt
	s_add_u32 s24, s74, s38
	s_addc_u32 s25, s75, 0
	global_load_dwordx4 v[124:127], v184, s[24:25] nt
	s_add_i32 s31, s31, 1
	s_mul_i32 s11, s31, s37
	s_lshl_b32 s12, s30, 9
	s_add_u32 s11, s11, s12
	s_add_u32 s74, s68, s11
	s_addc_u32 s75, s69, 0
	s_lshl_b32 s12, s31, 9
	s_add_u32 s80, s70, s12
	s_addc_u32 s81, s71, 0
	s_lshl_b32 s12, s38, 5
	global_load_dwordx2 v[176:177], v186, s[80:81]
	global_load_dwordx2 v[178:179], v186, s[80:81] offset:128
	global_load_dwordx2 v[180:181], v186, s[80:81] offset:256
	global_load_dwordx2 v[182:183], v186, s[80:81] offset:384
	global_load_dwordx4 v[128:131], v184, s[74:75] nt
	s_add_u32 s24, s74, s38
	s_addc_u32 s25, s75, 0
	global_load_dwordx4 v[132:135], v184, s[24:25] nt
	s_add_u32 s74, s74, s12
	s_addc_u32 s75, s75, 0
	global_load_dwordx4 v[136:139], v184, s[74:75] nt
	s_add_u32 s24, s74, s38
	s_addc_u32 s25, s75, 0
	global_load_dwordx4 v[140:143], v184, s[24:25] nt
	s_add_u32 s74, s74, s12
	s_addc_u32 s75, s75, 0
	global_load_dwordx4 v[144:147], v184, s[74:75] nt
	s_add_u32 s24, s74, s38
	s_addc_u32 s25, s75, 0
	global_load_dwordx4 v[148:151], v184, s[24:25] nt
	s_add_u32 s74, s74, s12
	s_addc_u32 s75, s75, 0
	global_load_dwordx4 v[152:155], v184, s[74:75] nt
	s_add_u32 s24, s74, s38
	s_addc_u32 s25, s75, 0
	global_load_dwordx4 v[156:159], v184, s[24:25] nt
	s_add_i32 s31, s31, 1
	s_waitcnt vmcnt(24)
	s_bitcmp1_b32 s41, 0
	s_cbranch_scc0 .Lcv_nomul0
	v_mul_f32_e32 v64, v64, v160
	v_mul_f32_e32 v65, v65, v160
	v_mul_f32_e32 v66, v66, v160
	v_mul_f32_e32 v67, v67, v160
	v_mul_f32_e32 v68, v68, v161
	v_mul_f32_e32 v69, v69, v161
	v_mul_f32_e32 v70, v70, v161
	v_mul_f32_e32 v71, v71, v161
	v_mul_f32_e32 v72, v72, v162
	v_mul_f32_e32 v73, v73, v162
	v_mul_f32_e32 v74, v74, v162
	v_mul_f32_e32 v75, v75, v162
	v_mul_f32_e32 v76, v76, v163
	v_mul_f32_e32 v77, v77, v163
	v_mul_f32_e32 v78, v78, v163
	v_mul_f32_e32 v79, v79, v163
	v_mul_f32_e32 v80, v80, v164
	v_mul_f32_e32 v81, v81, v164
	v_mul_f32_e32 v82, v82, v164
	v_mul_f32_e32 v83, v83, v164
	v_mul_f32_e32 v84, v84, v165
	v_mul_f32_e32 v85, v85, v165
	v_mul_f32_e32 v86, v86, v165
	v_mul_f32_e32 v87, v87, v165
	v_mul_f32_e32 v88, v88, v166
	v_mul_f32_e32 v89, v89, v166
	v_mul_f32_e32 v90, v90, v166
	v_mul_f32_e32 v91, v91, v166
	v_mul_f32_e32 v92, v92, v167
	v_mul_f32_e32 v93, v93, v167
	v_mul_f32_e32 v94, v94, v167
	v_mul_f32_e32 v95, v95, v167
; #define LAS __attribute__((address_space(3)))
; DI unsigned cvt_pk_bf16(float lo, float hi) { unsigned r; asm volatile("v_cvt_pk_bf16_f32 %0, %1, %2" : "=v"(r) : "v"(lo), "v"(hi)); return r; }
; template <bool GV_INTERLEAVE = false>
; DI void convert_chunk(const Ctx& cx, const float* __restrict__ src, bf16_t* __restrict__ dst, int K, int N, int tile0, int ntile, LAS unsigned char* lds, const float* __restrict__ gk = nullptr) {
;     ...
;     __syncthreads();
; #pragma unroll
;     for (int j = 0; j < 4; ++j)
; #pragma unroll
;       for (int i = 0; i < 4; ++i) L[(4 * n4 + i) * 66 + ((16 * j + kp) ^ ((n4 & 7) << 1))] = cvt_pk_bf16(v[j][0][i], v[j][1][i]);
;     if (c + 1 < ntile) { const int t2 = tile + 1, tn2 = t2 % tilesN, tk2 = t2 / tilesN;
; #pragma unroll
;       for (int j = 0; j < 4; ++j)
; #pragma unroll
;         for (int r = 0; r < 2; ++r) v[j][r] = __builtin_nontemporal_load((const f32x4*)(src + (size_t)(tk2 * 128 + 32 * j + 2 * kp + r) * N + tn2 * 128 + 4 * n4)); }
;     __syncthreads();
; #pragma unroll
;     for (int h2 = 0; h2 < 2; ++h2) {
;       const int rn = (tid >> 3) + 64 * h2, rc = tid & 7;
;       const int sw = ((rn >> 2) & 7) << 1;
;       u32x2 a0 = *(LAS u32x2*)(L + rn * 66 + ((8 * rc) ^ sw)), a1 = *(LAS u32x2*)(L + rn * 66 + ((8 * rc + 2) ^ sw));
;       u32x2 a2 = *(LAS u32x2*)(L + rn * 66 + ((8 * rc + 4) ^ sw)), a3 = *(LAS u32x2*)(L + rn * 66 + ((8 * rc + 6) ^ sw));
;       int drow = n0 + rn;
;       if (GV_INTERLEAVE) { const int half = N >> 1; const int isv = drow >= half ? 1 : 0; const int f = drow - isv * half; drow = (f >> 7) * 256 + isv * 128 + (f & 127); }
;       bf16_t* d = dst + (size_t)drow * K + k0 + 16 * rc;
;       *(u32x4*)d = (u32x4){a0.x, a0.y, a1.x, a1.y};
;       *(u32x4*)(d + 8) = (u32x4){a2.x, a2.y, a3.x, a3.y};
;     }
.Lcv_nomul0:
	v_cvt_pk_bf16_f32 v64, v64, v68
	ds_write_b32 v43, v64
	v_cvt_pk_bf16_f32 v65, v65, v69
	ds_write_b32 v43, v65 offset:264
	v_cvt_pk_bf16_f32 v66, v66, v70
	ds_write_b32 v43, v66 offset:528
	v_cvt_pk_bf16_f32 v67, v67, v71
	ds_write_b32 v43, v67 offset:792
	v_cvt_pk_bf16_f32 v72, v72, v76
	ds_write_b32 v43, v72 offset:64
	v_cvt_pk_bf16_f32 v73, v73, v77
	ds_write_b32 v43, v73 offset:328
	v_cvt_pk_bf16_f32 v74, v74, v78
	ds_write_b32 v43, v74 offset:592
	v_cvt_pk_bf16_f32 v75, v75, v79
	ds_write_b32 v43, v75 offset:856
	v_cvt_pk_bf16_f32 v80, v80, v84
	ds_write_b32 v43, v80 offset:128
	v_cvt_pk_bf16_f32 v81, v81, v85
	ds_write_b32 v43, v81 offset:392
	v_cvt_pk_bf16_f32 v82, v82, v86
	ds_write_b32 v43, v82 offset:656
	v_cvt_pk_bf16_f32 v83, v83, v87
	ds_write_b32 v43, v83 offset:920
	v_cvt_pk_bf16_f32 v88, v88, v92
	ds_write_b32 v43, v88 offset:192
	v_cvt_pk_bf16_f32 v89, v89, v93
	ds_write_b32 v43, v89 offset:456
	v_cvt_pk_bf16_f32 v90, v90, v94
	ds_write_b32 v43, v90 offset:720
	v_cvt_pk_bf16_f32 v91, v91, v95
	ds_write_b32 v43, v91 offset:984
	s_mul_i32 s11, s31, s37
	s_lshl_b32 s12, s30, 9
	s_add_u32 s11, s11, s12
	s_add_u32 s74, s68, s11
	s_addc_u32 s75, s69, 0
	s_lshl_b32 s12, s31, 9
	s_add_u32 s80, s70, s12
	s_addc_u32 s81, s71, 0
	s_lshl_b32 s12, s38, 5
	global_load_dwordx2 v[160:161], v186, s[80:81]
	global_load_dwordx2 v[162:163], v186, s[80:81] offset:128
	global_load_dwordx2 v[164:165], v186, s[80:81] offset:256
	global_load_dwordx2 v[166:167], v186, s[80:81] offset:384
	global_load_dwordx4 v[64:67], v184, s[74:75] nt
	s_add_u32 s24, s74, s38
	s_addc_u32 s25, s75, 0
	global_load_dwordx4 v[68:71], v184, s[24:25] nt
	s_add_u32 s74, s74, s12
	s_addc_u32 s75, s75, 0
	global_load_dwordx4 v[72:75], v184, s[74:75] nt
	s_add_u32 s24, s74, s38
	s_addc_u32 s25, s75, 0
	global_load_dwordx4 v[76:79], v184, s[24:25] nt
	s_add_u32 s74, s74, s12
	s_addc_u32 s75, s75, 0
	global_load_dwordx4 v[80:83], v184, s[74:75] nt
	s_add_u32 s24, s74, s38
	s_addc_u32 s25, s75, 0
	global_load_dwordx4 v[84:87], v184, s[24:25] nt
	s_add_u32 s74, s74, s12
	s_addc_u32 s75, s75, 0
	global_load_dwordx4 v[88:91], v184, s[74:75] nt
	s_add_u32 s24, s74, s38
	s_addc_u32 s25, s75, 0
	global_load_dwordx4 v[92:95], v184, s[24:25] nt
	s_add_i32 s31, s31, 1
	s_waitcnt lgkmcnt(0)
	s_barrier
	ds_read_b64 v[188:189], v42
	ds_read_b64 v[190:191], v47
	ds_read_b64 v[192:193], v48
	ds_read_b64 v[194:195], v49
	ds_read_b64 v[196:197], v42 offset:16896
	ds_read_b64 v[198:199], v47 offset:16896
	ds_read_b64 v[200:201], v48 offset:16896
	ds_read_b64 v[202:203], v49 offset:16896
	s_mov_b32 s11, s42
	s_bitcmp1_b32 s41, 1
	s_cbranch_scc0 .Lcv_ni0
	s_cmpk_ge_i32 s42, 44
	s_cselect_b32 s12, 44, 0
	s_cselect_b32 s22, 1, 0
	s_sub_i32 s11, s42, s12
	s_lshl_b32 s11, s11, 1
	s_or_b32 s11, s11, s22
.Lcv_ni0:
	s_mul_i32 s11, s11, s36
	s_lshl_b32 s12, s43, 8
	s_add_u32 s11, s11, s12
	s_add_u32 s76, s72, s11
	s_addc_u32 s77, s73, 0
	s_add_u32 s78, s76, s82
	s_addc_u32 s79, s77, 0
	s_add_i32 s43, s43, 1
	s_waitcnt lgkmcnt(6)
	global_store_dwordx4 v185, v[188:191], s[76:77]
	s_waitcnt lgkmcnt(4)
	global_store_dwordx4 v185, v[192:195], s[76:77] offset:16
	s_waitcnt lgkmcnt(2)
	global_store_dwordx4 v185, v[196:199], s[78:79]
	s_waitcnt lgkmcnt(0)
	global_store_dwordx4 v185, v[200:203], s[78:79] offset:16
	s_waitcnt vmcnt(28)
	s_bitcmp1_b32 s41, 0
	s_cbranch_scc0 .Lcv_nomul1
	v_mul_f32_e32 v96, v96, v168
	v_mul_f32_e32 v97, v97, v168
	v_mul_f32_e32 v98, v98, v168
	v_mul_f32_e32 v99, v99, v168
	v_mul_f32_e32 v100, v100, v169
	v_mul_f32_e32 v101, v101, v169
	v_mul_f32_e32 v102, v102, v169
	v_mul_f32_e32 v103, v103, v169
	v_mul_f32_e32 v104, v104, v170
	v_mul_f32_e32 v105, v105, v170
	v_mul_f32_e32 v106, v106, v170
	v_mul_f32_e32 v107, v107, v170
	v_mul_f32_e32 v108, v108, v171
	v_mul_f32_e32 v109, v109, v171
	v_mul_f32_e32 v110, v110, v171
	v_mul_f32_e32 v111, v111, v171
	v_mul_f32_e32 v112, v112, v172
	v_mul_f32_e32 v113, v113, v172
	v_mul_f32_e32 v114, v114, v172
	v_mul_f32_e32 v115, v115, v172
	v_mul_f32_e32 v116, v116, v173
	v_mul_f32_e32 v117, v117, v173
	v_mul_f32_e32 v118, v118, v173
	v_mul_f32_e32 v119, v119, v173
	v_mul_f32_e32 v120, v120, v174
	v_mul_f32_e32 v121, v121, v174
	v_mul_f32_e32 v122, v122, v174
	v_mul_f32_e32 v123, v123, v174
	v_mul_f32_e32 v124, v124, v175
	v_mul_f32_e32 v125, v125, v175
	v_mul_f32_e32 v126, v126, v175
	v_mul_f32_e32 v127, v127, v175
.Lcv_nomul1:
	v_cvt_pk_bf16_f32 v96, v96, v100
	ds_write_b32 v43, v96 offset:33792
	v_cvt_pk_bf16_f32 v97, v97, v101
	ds_write_b32 v43, v97 offset:34056
	v_cvt_pk_bf16_f32 v98, v98, v102
	ds_write_b32 v43, v98 offset:34320
	v_cvt_pk_bf16_f32 v99, v99, v103
	ds_write_b32 v43, v99 offset:34584
	v_cvt_pk_bf16_f32 v104, v104, v108
	ds_write_b32 v43, v104 offset:33856
	v_cvt_pk_bf16_f32 v105, v105, v109
	ds_write_b32 v43, v105 offset:34120
	v_cvt_pk_bf16_f32 v106, v106, v110
	ds_write_b32 v43, v106 offset:34384
	v_cvt_pk_bf16_f32 v107, v107, v111
	ds_write_b32 v43, v107 offset:34648
	v_cvt_pk_bf16_f32 v112, v112, v116
	ds_write_b32 v43, v112 offset:33920
	v_cvt_pk_bf16_f32 v113, v113, v117
	ds_write_b32 v43, v113 offset:34184
	v_cvt_pk_bf16_f32 v114, v114, v118
	ds_write_b32 v43, v114 offset:34448
	v_cvt_pk_bf16_f32 v115, v115, v119
	ds_write_b32 v43, v115 offset:34712
	v_cvt_pk_bf16_f32 v120, v120, v124
	ds_write_b32 v43, v120 offset:33984
	v_cvt_pk_bf16_f32 v121, v121, v125
	ds_write_b32 v43, v121 offset:34248
	v_cvt_pk_bf16_f32 v122, v122, v126
	ds_write_b32 v43, v122 offset:34512
	v_cvt_pk_bf16_f32 v123, v123, v127
	ds_write_b32 v43, v123 offset:34776
	s_waitcnt lgkmcnt(0)
	s_barrier
	ds_read_b64 v[188:189], v42 offset:33792
	ds_read_b64 v[190:191], v47 offset:33792
	ds_read_b64 v[192:193], v48 offset:33792
	ds_read_b64 v[194:195], v49 offset:33792
	ds_read_b64 v[196:197], v42 offset:50688
	ds_read_b64 v[198:199], v47 offset:50688
	ds_read_b64 v[200:201], v48 offset:50688
	ds_read_b64 v[202:203], v49 offset:50688
	s_mov_b32 s11, s42
	s_bitcmp1_b32 s41, 1
	s_cbranch_scc0 .Lcv_ni1
	s_cmpk_ge_i32 s42, 44
	s_cselect_b32 s12, 44, 0
	s_cselect_b32 s22, 1, 0
	s_sub_i32 s11, s42, s12
	s_lshl_b32 s11, s11, 1
	s_or_b32 s11, s11, s22
; #define LAS __attribute__((address_space(3)))
; DI unsigned cvt_pk_bf16(float lo, float hi) { unsigned r; asm volatile("v_cvt_pk_bf16_f32 %0, %1, %2" : "=v"(r) : "v"(lo), "v"(hi)); return r; }
; template <bool GV_INTERLEAVE = false>
; DI void convert_chunk(const Ctx& cx, const float* __restrict__ src, bf16_t* __restrict__ dst, int K, int N, int tile0, int ntile, LAS unsigned char* lds, const float* __restrict__ gk = nullptr) {
;     ...
;     __syncthreads();
; #pragma unroll
;     for (int j = 0; j < 4; ++j)
; #pragma unroll
;       for (int i = 0; i < 4; ++i) L[(4 * n4 + i) * 66 + ((16 * j + kp) ^ ((n4 & 7) << 1))] = cvt_pk_bf16(v[j][0][i], v[j][1][i]);
;     if (c + 1 < ntile) { const int t2 = tile + 1, tn2 = t2 % tilesN, tk2 = t2 / tilesN;
; #pragma unroll
;       for (int j = 0; j < 4; ++j)
; #pragma unroll
;         for (int r = 0; r < 2; ++r) v[j][r] = __builtin_nontemporal_load((const f32x4*)(src + (size_t)(tk2 * 128 + 32 * j + 2 * kp + r) * N + tn2 * 128 + 4 * n4)); }
;     __syncthreads();
; #pragma unroll
;     for (int h2 = 0; h2 < 2; ++h2) {
;       const int rn = (tid >> 3) + 64 * h2, rc = tid & 7;
;       const int sw = ((rn >> 2) & 7) << 1;
;       u32x2 a0 = *(LAS u32x2*)(L + rn * 66 + ((8 * rc) ^ sw)), a1 = *(LAS u32x2*)(L + rn * 66 + ((8 * rc + 2) ^ sw));
;       u32x2 a2 = *(LAS u32x2*)(L + rn * 66 + ((8 * rc + 4) ^ sw)), a3 = *(LAS u32x2*)(L + rn * 66 + ((8 * rc + 6) ^ sw));
;       int drow = n0 + rn;
;       if (GV_INTERLEAVE) { const int half = N >> 1; const int isv = drow >= half ? 1 : 0; const int f = drow - isv * half; drow = (f >> 7) * 256 + isv * 128 + (f & 127); }
;       bf16_t* d = dst + (size_t)drow * K + k0 + 16 * rc;
;       *(u32x4*)d = (u32x4){a0.x, a0.y, a1.x, a1.y};
;       *(u32x4*)(d + 8) = (u32x4){a2.x, a2.y, a3.x, a3.y};
;     }
.Lcv_ni1:
	s_mul_i32 s11, s11, s36
	s_lshl_b32 s12, s43, 8
	s_add_u32 s11, s11, s12
	s_add_u32 s76, s72, s11
	s_addc_u32 s77, s73, 0
	s_add_u32 s78, s76, s82
	s_addc_u32 s79, s77, 0
	s_add_i32 s43, s43, 1
	s_waitcnt lgkmcnt(6)
	global_store_dwordx4 v185, v[188:191], s[76:77]
	s_waitcnt lgkmcnt(4)
	global_store_dwordx4 v185, v[192:195], s[76:77] offset:16
	s_waitcnt lgkmcnt(2)
	global_store_dwordx4 v185, v[196:199], s[78:79]
	s_waitcnt lgkmcnt(0)
	global_store_dwordx4 v185, v[200:203], s[78:79] offset:16
	s_waitcnt vmcnt(20)
	s_bitcmp1_b32 s41, 0
	s_cbranch_scc0 .Lcv_nomul2
	v_mul_f32_e32 v128, v128, v176
	v_mul_f32_e32 v129, v129, v176
	v_mul_f32_e32 v130, v130, v176
	v_mul_f32_e32 v131, v131, v176
	v_mul_f32_e32 v132, v132, v177
	v_mul_f32_e32 v133, v133, v177
	v_mul_f32_e32 v134, v134, v177
	v_mul_f32_e32 v135, v135, v177
	v_mul_f32_e32 v136, v136, v178
	v_mul_f32_e32 v137, v137, v178
	v_mul_f32_e32 v138, v138, v178
	v_mul_f32_e32 v139, v139, v178
	v_mul_f32_e32 v140, v140, v179
	v_mul_f32_e32 v141, v141, v179
	v_mul_f32_e32 v142, v142, v179
	v_mul_f32_e32 v143, v143, v179
	v_mul_f32_e32 v144, v144, v180
	v_mul_f32_e32 v145, v145, v180
	v_mul_f32_e32 v146, v146, v180
	v_mul_f32_e32 v147, v147, v180
	v_mul_f32_e32 v148, v148, v181
	v_mul_f32_e32 v149, v149, v181
	v_mul_f32_e32 v150, v150, v181
	v_mul_f32_e32 v151, v151, v181
	v_mul_f32_e32 v152, v152, v182
	v_mul_f32_e32 v153, v153, v182
	v_mul_f32_e32 v154, v154, v182
	v_mul_f32_e32 v155, v155, v182
	v_mul_f32_e32 v156, v156, v183
	v_mul_f32_e32 v157, v157, v183
	v_mul_f32_e32 v158, v158, v183
	v_mul_f32_e32 v159, v159, v183
.Lcv_nomul2:
	v_cvt_pk_bf16_f32 v128, v128, v132
	ds_write_b32 v43, v128
	v_cvt_pk_bf16_f32 v129, v129, v133
	ds_write_b32 v43, v129 offset:264
	v_cvt_pk_bf16_f32 v130, v130, v134
	ds_write_b32 v43, v130 offset:528
	v_cvt_pk_bf16_f32 v131, v131, v135
	ds_write_b32 v43, v131 offset:792
	v_cvt_pk_bf16_f32 v136, v136, v140
	ds_write_b32 v43, v136 offset:64
	v_cvt_pk_bf16_f32 v137, v137, v141
	ds_write_b32 v43, v137 offset:328
	v_cvt_pk_bf16_f32 v138, v138, v142
	ds_write_b32 v43, v138 offset:592
	v_cvt_pk_bf16_f32 v139, v139, v143
	ds_write_b32 v43, v139 offset:856
	v_cvt_pk_bf16_f32 v144, v144, v148
	ds_write_b32 v43, v144 offset:128
	v_cvt_pk_bf16_f32 v145, v145, v149
	ds_write_b32 v43, v145 offset:392
	v_cvt_pk_bf16_f32 v146, v146, v150
	ds_write_b32 v43, v146 offset:656
	v_cvt_pk_bf16_f32 v147, v147, v151
	ds_write_b32 v43, v147 offset:920
	v_cvt_pk_bf16_f32 v152, v152, v156
	ds_write_b32 v43, v152 offset:192
	v_cvt_pk_bf16_f32 v153, v153, v157
	ds_write_b32 v43, v153 offset:456
	v_cvt_pk_bf16_f32 v154, v154, v158
	ds_write_b32 v43, v154 offset:720
	v_cvt_pk_bf16_f32 v155, v155, v159
	ds_write_b32 v43, v155 offset:984
	s_waitcnt lgkmcnt(0)
	s_barrier
	ds_read_b64 v[188:189], v42
	ds_read_b64 v[190:191], v47
	ds_read_b64 v[192:193], v48
	ds_read_b64 v[194:195], v49
	ds_read_b64 v[196:197], v42 offset:16896
	ds_read_b64 v[198:199], v47 offset:16896
	ds_read_b64 v[200:201], v48 offset:16896
	ds_read_b64 v[202:203], v49 offset:16896
	s_mov_b32 s11, s42
	s_bitcmp1_b32 s41, 1
	s_cbranch_scc0 .Lcv_ni2
	s_cmpk_ge_i32 s42, 44
	s_cselect_b32 s12, 44, 0
	s_cselect_b32 s22, 1, 0
	s_sub_i32 s11, s42, s12
	s_lshl_b32 s11, s11, 1
	s_or_b32 s11, s11, s22
.Lcv_ni2:
	s_mul_i32 s11, s11, s36
	s_lshl_b32 s12, s43, 8
	s_add_u32 s11, s11, s12
	s_add_u32 s76, s72, s11
	s_addc_u32 s77, s73, 0
	s_add_u32 s78, s76, s82
	s_addc_u32 s79, s77, 0
	s_add_i32 s43, s43, 1
	s_waitcnt lgkmcnt(6)
	global_store_dwordx4 v185, v[188:191], s[76:77]
	s_waitcnt lgkmcnt(4)
	global_store_dwordx4 v185, v[192:195], s[76:77] offset:16
	s_waitcnt lgkmcnt(2)
	global_store_dwordx4 v185, v[196:199], s[78:79]
	s_waitcnt lgkmcnt(0)
	global_store_dwordx4 v185, v[200:203], s[78:79] offset:16
	s_waitcnt vmcnt(12)
	s_bitcmp1_b32 s41, 0
	s_cbranch_scc0 .Lcv_nomul3
	v_mul_f32_e32 v64, v64, v160
	v_mul_f32_e32 v65, v65, v160
	v_mul_f32_e32 v66, v66, v160
	v_mul_f32_e32 v67, v67, v160
	v_mul_f32_e32 v68, v68, v161
	v_mul_f32_e32 v69, v69, v161
	v_mul_f32_e32 v70, v70, v161
	v_mul_f32_e32 v71, v71, v161
	v_mul_f32_e32 v72, v72, v162
	v_mul_f32_e32 v73, v73, v162
	v_mul_f32_e32 v74, v74, v162
	v_mul_f32_e32 v75, v75, v162
	v_mul_f32_e32 v76, v76, v163
	v_mul_f32_e32 v77, v77, v163
	v_mul_f32_e32 v78, v78, v163
	v_mul_f32_e32 v79, v79, v163
	v_mul_f32_e32 v80, v80, v164
	v_mul_f32_e32 v81, v81, v164
	v_mul_f32_e32 v82, v82, v164
	v_mul_f32_e32 v83, v83, v164
	v_mul_f32_e32 v84, v84, v165
	v_mul_f32_e32 v85, v85, v165
	v_mul_f32_e32 v86, v86, v165
	v_mul_f32_e32 v87, v87, v165
	v_mul_f32_e32 v88, v88, v166
	v_mul_f32_e32 v89, v89, v166
	v_mul_f32_e32 v90, v90, v166
	v_mul_f32_e32 v91, v91, v166
	v_mul_f32_e32 v92, v92, v167
	v_mul_f32_e32 v93, v93, v167
	v_mul_f32_e32 v94, v94, v167
	v_mul_f32_e32 v95, v95, v167
.Lcv_nomul3:
	v_cvt_pk_bf16_f32 v64, v64, v68
	ds_write_b32 v43, v64 offset:33792
	v_cvt_pk_bf16_f32 v65, v65, v69
	ds_write_b32 v43, v65 offset:34056
	v_cvt_pk_bf16_f32 v66, v66, v70
	ds_write_b32 v43, v66 offset:34320
	v_cvt_pk_bf16_f32 v67, v67, v71
	ds_write_b32 v43, v67 offset:34584
	v_cvt_pk_bf16_f32 v72, v72, v76
	ds_write_b32 v43, v72 offset:33856
	v_cvt_pk_bf16_f32 v73, v73, v77
	ds_write_b32 v43, v73 offset:34120
	v_cvt_pk_bf16_f32 v74, v74, v78
	ds_write_b32 v43, v74 offset:34384
	v_cvt_pk_bf16_f32 v75, v75, v79
	ds_write_b32 v43, v75 offset:34648
	v_cvt_pk_bf16_f32 v80, v80, v84
	ds_write_b32 v43, v80 offset:33920
	v_cvt_pk_bf16_f32 v81, v81, v85
	ds_write_b32 v43, v81 offset:34184
	v_cvt_pk_bf16_f32 v82, v82, v86
	ds_write_b32 v43, v82 offset:34448
	v_cvt_pk_bf16_f32 v83, v83, v87
	ds_write_b32 v43, v83 offset:34712
	v_cvt_pk_bf16_f32 v88, v88, v92
	ds_write_b32 v43, v88 offset:33984
	v_cvt_pk_bf16_f32 v89, v89, v93
	ds_write_b32 v43, v89 offset:34248
	v_cvt_pk_bf16_f32 v90, v90, v94
	ds_write_b32 v43, v90 offset:34512
	v_cvt_pk_bf16_f32 v91, v91, v95
	ds_write_b32 v43, v91 offset:34776
	s_waitcnt lgkmcnt(0)
	s_barrier
	ds_read_b64 v[188:189], v42 offset:33792
	ds_read_b64 v[190:191], v47 offset:33792
	ds_read_b64 v[192:193], v48 offset:33792
	ds_read_b64 v[194:195], v49 offset:33792
	ds_read_b64 v[196:197], v42 offset:50688
	ds_read_b64 v[198:199], v47 offset:50688
	ds_read_b64 v[200:201], v48 offset:50688
	ds_read_b64 v[202:203], v49 offset:50688
	s_mov_b32 s11, s42
	s_bitcmp1_b32 s41, 1
	s_cbranch_scc0 .Lcv_ni3
	s_cmpk_ge_i32 s42, 44
	s_cselect_b32 s12, 44, 0
	s_cselect_b32 s22, 1, 0
	s_sub_i32 s11, s42, s12
	s_lshl_b32 s11, s11, 1
	s_or_b32 s11, s11, s22
.Lcv_ni3:
	s_mul_i32 s11, s11, s36
	s_lshl_b32 s12, s43, 8
	s_add_u32 s11, s11, s12
	s_add_u32 s76, s72, s11
	s_addc_u32 s77, s73, 0
	s_add_u32 s78, s76, s82
	s_addc_u32 s79, s77, 0
	s_add_i32 s43, s43, 1
	s_waitcnt lgkmcnt(6)
	global_store_dwordx4 v185, v[188:191], s[76:77]
	s_waitcnt lgkmcnt(4)
	global_store_dwordx4 v185, v[192:195], s[76:77] offset:16
	s_waitcnt lgkmcnt(2)
	global_store_dwordx4 v185, v[196:199], s[78:79]
	s_waitcnt lgkmcnt(0)
	global_store_dwordx4 v185, v[200:203], s[78:79] offset:16
	s_branch .LBB0_157
